# prep phase norm-item rebalance (compress WGs take 1 item/wave, others 4) on top of P4 order remap
# speedup vs baseline: 1.0202x; 1.0060x over previous
; DI void prep_norm_item(const Params& P, int l, int it, int lane) {
;     bf16_t* hb = (bf16_t*)(P.ws + WS_H);
;     const int blk = it / 10, sp10 = it % 10, sp = sp10 < 4 ? 4 + sp10 : (sp10 < 8 ? 8 + sp10 : 12 + sp10), sub = lane & 7, tl = lane >> 3;
;     int col; const float* g; bool diff = false, km = false; float qs = 1.0f;
;     if (sp < 4) { col = C_DFQ + 64 * sp; g = P.in[3] + l * 32; diff = true; qs = 0.17677669529663687f * LOG2E_; }
;     else if (sp < 8) { col = C_DFK + 64 * (sp - 4); g = P.in[4] + l * 32; diff = true; }
;     else if (sp < 12) { col = C_MBQ + 64 * (sp - 8); g = P.in[7] + l * 64; qs = 0.125f * LOG2E_; }
;     else if (sp < 16) { col = C_MBK + 64 * (sp - 12); g = P.in[8] + l * 64; km = true; }
;     else if (sp < 20) { col = C_NSQ + 64 * (sp - 16); g = P.in[9] + l * 64; qs = 0.125f * LOG2E_; }
;     else if (sp == 20) { col = C_KS; g = P.in[10] + (l * 3 + 1) * 64; }
;     else { col = C_KW; g = P.in[10] + (l * 3 + 2) * 64; }
;     float gv[8], inv[8], kacc[8];
; #pragma unroll
;     for (int e = 0; e < 8; ++e) { gv[e] = (diff ? g[8 * (sub & 3) + e] : g[8 * sub + e]); kacc[e] = 0.f;
;         inv[e] = diff ? exp2f(-(float)(e & 3) * 0.25f * LOG2_THETA) : exp2f(-(float)e * 0.125f * LOG2_THETA); }
;     u32x4* p0 = (u32x4*)(hb + (size_t)(blk * 64 + tl) * NIN + col + 8 * sub);
; DI void prep_phase(const Params& P, int l, LAS unsigned char* lds, int G, int bx, int gw, int NGW, int wave, int lane) {
;     ...
;     for (int it = gw; it < 512 * 10; it += NGW) prep_norm_item(P, l, it, lane);
.LBB0_333:
	s_cmp_lg_u32 s96, 0x100
	s_cbranch_scc1 .Lprep_orig
	s_lshl_b32 s100, s2, 3
	s_add_i32 s25, s25, s100
	s_movk_i32 s100, 0x1400
	s_cmp_lt_u32 s2, 0x80
	s_cbranch_scc0 .Lprep_l1
	s_movk_i32 s100, 0x400
.Lprep_l1:
	s_movk_i32 s101, 0x400
	s_branch .Lprep_go
.Lprep_orig:
	s_add_i32 s25, s25, s79
	s_movk_i32 s100, 0x1400
	s_mov_b32 s101, s3
.Lprep_go:
	s_cmp_ge_i32 s25, s100
	s_cbranch_scc1 .LBB0_438
	s_mov_b32 s45, s23
	v_readlane_b32 s56, v255, 2
	s_lshl_b32 s22, s74, 6
	s_lshl_b32 s0, s74, 5
	s_lshl_b64 s[10:11], s[44:45], 2
	v_readlane_b32 s70, v255, 16
	v_readlane_b32 s62, v255, 8
	v_readlane_b32 s71, v255, 17
	s_add_u32 s27, s70, s10
	v_readlane_b32 s68, v255, 14
	s_addc_u32 s62, s71, s11
	s_lshl_b64 s[10:11], s[22:23], 2
	v_readlane_b32 s69, v255, 15
	s_add_u32 s48, s68, s10
	v_readlane_b32 s66, v255, 12
	s_addc_u32 s49, s69, s11
	v_readlane_b32 s67, v255, 13
	s_add_u32 s50, s66, s10
	v_readlane_b32 s64, v255, 10
	s_addc_u32 s51, s67, s11
	s_mov_b32 s1, s23
	v_readlane_b32 s65, v255, 11
	s_add_u32 s52, s64, s10
	v_readlane_b32 s58, v255, 4
	s_addc_u32 s53, s65, s11
	s_lshl_b64 s[0:1], s[0:1], 2
	v_readlane_b32 s59, v255, 5
	s_add_u32 s54, s58, s0
	s_addc_u32 s55, s59, s1
	v_readlane_b32 s57, v255, 3
	s_add_u32 s56, s56, s0
	v_and_b32_e32 v0, 7, v87
	v_lshlrev_b32_e32 v1, 3, v86
	s_addc_u32 s57, s57, s1
	v_readlane_b32 s0, v254, 7
	v_and_b32_e32 v94, 24, v1
	v_lshlrev_b32_e32 v1, 2, v86
	v_and_b32_e32 v2, 3, v87
	v_lshlrev_b32_e32 v168, 5, v0
	v_readlane_b32 s1, v254, 8
	v_lshrrev_b32_e32 v37, 3, v86
	v_lshlrev_b32_e32 v36, 3, v0
	v_xor_b32_e32 v95, 4, v1
	v_xor_b32_e32 v96, 8, v1
	v_xor_b32_e32 v97, 16, v1
	v_cmp_gt_u32_e64 s[36:37], 2, v0
	v_cmp_eq_u32_e64 s[38:39], 0, v0
	v_cmp_eq_u32_e64 s[40:41], 0, v2
	v_xor_b32_e32 v98, 32, v1
	v_xor_b32_e32 v99, 64, v1
	v_cmp_gt_u32_e64 s[42:43], 8, v86
	v_lshl_add_u64 v[38:39], s[0:1], 0, v[168:169]
	v_readlane_b32 s60, v255, 6
	v_readlane_b32 s61, v255, 7
	v_readlane_b32 s63, v255, 9
	s_branch .LBB0_337

; DI void prep_phase(const Params& P, int l, LAS unsigned char* lds, int G, int bx, int gw, int NGW, int wave, int lane) {
;     ...
;     for (int it = gw; it < 512 * 10; it += NGW) prep_norm_item(P, l, it, lane);
.LBB0_336:
	s_add_i32 s25, s25, s101
	s_cmp_lt_i32 s25, s100
	s_cbranch_scc0 .LBB0_438

; __global__ void __launch_bounds__(NWAVES * 64 LB2) fwd_kernel(Params P) {
	.amdhsa_kernel _Z10fwd_kernel6Params
		.amdhsa_group_segment_fixed_size 0
		.amdhsa_private_segment_fixed_size 0
		.amdhsa_kernarg_size 440
		.amdhsa_user_sgpr_count 2
		.amdhsa_user_sgpr_dispatch_ptr 0
		.amdhsa_user_sgpr_queue_ptr 0
		.amdhsa_user_sgpr_kernarg_segment_ptr 1
		.amdhsa_user_sgpr_dispatch_id 0
		.amdhsa_user_sgpr_kernarg_preload_length 0
		.amdhsa_user_sgpr_kernarg_preload_offset 0
		.amdhsa_user_sgpr_private_segment_size 0
		.amdhsa_uses_dynamic_stack 0
		.amdhsa_enable_private_segment 0
		.amdhsa_system_sgpr_workgroup_id_x 1
		.amdhsa_system_sgpr_workgroup_id_y 0
		.amdhsa_system_sgpr_workgroup_id_z 0
		.amdhsa_system_sgpr_workgroup_info 0
		.amdhsa_system_vgpr_workitem_id 2
		.amdhsa_next_free_vgpr 256
		.amdhsa_next_free_sgpr 102
		.amdhsa_accum_offset 256
		.amdhsa_reserve_vcc 1
		.amdhsa_float_round_mode_32 0
		.amdhsa_float_round_mode_16_64 0
		.amdhsa_float_denorm_mode_32 3
		.amdhsa_float_denorm_mode_16_64 3
		.amdhsa_dx10_clamp 1
		.amdhsa_ieee_mode 1
		.amdhsa_fp16_overflow 0
		.amdhsa_tg_split 0
		.amdhsa_exception_fp_ieee_invalid_op 0
		.amdhsa_exception_fp_denorm_src 0
		.amdhsa_exception_fp_ieee_div_zero 0
		.amdhsa_exception_fp_ieee_overflow 0
		.amdhsa_exception_fp_ieee_underflow 0
		.amdhsa_exception_fp_ieee_inexact 0
		.amdhsa_exception_int_div_zero 0
	.end_amdhsa_kernel

; __global__ void __launch_bounds__(NWAVES * 64 LB2) fwd_kernel(Params P) {
amdhsa.kernels:
  - .agpr_count:     0
    .args:
      - .offset:         0
        .size:           184
        .value_kind:     by_value
      - .offset:         184
        .size:           4
        .value_kind:     hidden_block_count_x
      - .offset:         188
        .size:           4
        .value_kind:     hidden_block_count_y
      - .offset:         192
        .size:           4
        .value_kind:     hidden_block_count_z
      - .offset:         196
        .size:           2
        .value_kind:     hidden_group_size_x
      - .offset:         198
        .size:           2
        .value_kind:     hidden_group_size_y
      - .offset:         200
        .size:           2
        .value_kind:     hidden_group_size_z
      - .offset:         202
        .size:           2
        .value_kind:     hidden_remainder_x
      - .offset:         204
        .size:           2
        .value_kind:     hidden_remainder_y
      - .offset:         206
        .size:           2
        .value_kind:     hidden_remainder_z
      - .offset:         224
        .size:           8
        .value_kind:     hidden_global_offset_x
      - .offset:         232
        .size:           8
        .value_kind:     hidden_global_offset_y
      - .offset:         240
        .size:           8
        .value_kind:     hidden_global_offset_z
      - .offset:         248
        .size:           2
        .value_kind:     hidden_grid_dims
      - .offset:         272
        .size:           8
        .value_kind:     hidden_multigrid_sync_arg
      - .offset:         304
        .size:           4
        .value_kind:     hidden_dynamic_lds_size
    .group_segment_fixed_size: 0
    .kernarg_segment_align: 8
    .kernarg_segment_size: 440
    .language:       OpenCL C
    .language_version:
      - 2
      - 0
    .max_flat_workgroup_size: 512
    .name:           _Z10fwd_kernel6Params
    .private_segment_fixed_size: 0
    .sgpr_count:     108
    .sgpr_spill_count: 161
    .symbol:         _Z10fwd_kernel6Params.kd
    .uniform_work_group_size: 1
    .uses_dynamic_stack: false
    .vgpr_count:     256
    .vgpr_spill_count: 0
    .wavefront_size: 64
